# norm row-sum all-reduce: 4 row-DPP adds + v_permlane16/32_swap instead of six ds_bpermute hops (no LDS crossbar round trips)
# speedup vs baseline: 1.0028x; 1.0028x over previous
.LBB0_20:
	global_load_dwordx2 v[80:81], v[64:65], off nt
	global_load_dwordx2 v[68:69], v[64:65], off offset:512 nt
	global_load_dwordx4 v[52:55], v[66:67], off offset:-3072 nt
	global_load_dwordx4 v[48:51], v[66:67], off offset:-2048 nt
	global_load_dwordx2 v[70:71], v[64:65], off offset:1024 nt
	global_load_dwordx4 v[60:63], v[66:67], off offset:-1024 nt
	global_load_dwordx4 v[56:59], v[66:67], off nt
	global_load_dwordx2 v[82:83], v[64:65], off offset:1536 nt
	v_add_co_u32_e32 v84, vcc, 0xec800000, v64
	v_add_co_u32_e64 v86, s[0:1], s60, v64
	s_nop 0
	v_addc_co_u32_e32 v85, vcc, -1, v65, vcc
	v_addc_co_u32_e64 v87, s[0:1], -1, v65, s[0:1]
	global_load_dwordx2 v[84:85], v[84:85], off nt
	s_nop 0
	global_load_dwordx2 v[88:89], v[86:87], off offset:-3584 nt
	global_load_dwordx2 v[90:91], v[86:87], off offset:-3072 nt
	s_nop 0
	global_load_dwordx2 v[86:87], v[86:87], off offset:-2560 nt
	v_add_u32_e32 v79, 32, v79
	v_cmp_ge_i32_e32 vcc, v79, v72
	s_or_b64 s[16:17], vcc, s[16:17]
	v_lshl_add_u64 v[64:65], v[64:65], 0, s[12:13]
	s_waitcnt vmcnt(11)
	v_lshlrev_b32_e32 v92, 16, v80
	v_and_b32_e32 v93, 0xffff0000, v80
	v_lshlrev_b32_e32 v80, 16, v81
	v_and_b32_e32 v81, 0xffff0000, v81
	s_waitcnt vmcnt(10)
	v_lshlrev_b32_e32 v94, 16, v68
	v_and_b32_e32 v95, 0xffff0000, v68
	v_lshlrev_b32_e32 v68, 16, v69
	v_and_b32_e32 v69, 0xffff0000, v69
	s_waitcnt vmcnt(7)
	v_lshlrev_b32_e32 v96, 16, v70
	v_and_b32_e32 v97, 0xffff0000, v70
	v_lshlrev_b32_e32 v70, 16, v71
	v_and_b32_e32 v71, 0xffff0000, v71
	s_waitcnt vmcnt(4)
	v_lshlrev_b32_e32 v98, 16, v82
	v_and_b32_e32 v99, 0xffff0000, v82
	v_lshlrev_b32_e32 v82, 16, v83
	v_and_b32_e32 v83, 0xffff0000, v83
	v_pk_fma_f32 v[52:53], v[44:45], v[92:93], v[52:53]
	v_pk_fma_f32 v[54:55], v[46:47], v[80:81], v[54:55]
	v_pk_fma_f32 v[48:49], v[40:41], v[94:95], v[48:49]
	v_pk_fma_f32 v[50:51], v[42:43], v[68:69], v[50:51]
	v_pk_fma_f32 v[62:63], v[30:31], v[70:71], v[62:63]
	v_pk_fma_f32 v[58:59], v[26:27], v[82:83], v[58:59]
	s_waitcnt vmcnt(3)
	v_lshlrev_b32_e32 v68, 16, v84
	v_and_b32_e32 v69, 0xffff0000, v84
	v_lshlrev_b32_e32 v70, 16, v85
	v_and_b32_e32 v71, 0xffff0000, v85
	s_waitcnt vmcnt(2)
	v_lshlrev_b32_e32 v80, 16, v88
	v_and_b32_e32 v81, 0xffff0000, v88
	v_lshlrev_b32_e32 v82, 16, v89
	v_and_b32_e32 v83, 0xffff0000, v89
	v_pk_fma_f32 v[52:53], v[36:37], v[68:69], v[52:53]
	v_pk_fma_f32 v[54:55], v[38:39], v[70:71], v[54:55]
	v_pk_fma_f32 v[48:49], v[32:33], v[80:81], v[48:49]
	v_pk_fma_f32 v[50:51], v[34:35], v[82:83], v[50:51]
	v_pk_fma_f32 v[60:61], v[28:29], v[96:97], v[60:61]
	s_waitcnt vmcnt(1)
	v_lshlrev_b32_e32 v84, 16, v90
	v_and_b32_e32 v85, 0xffff0000, v90
	v_lshlrev_b32_e32 v88, 16, v91
	v_and_b32_e32 v89, 0xffff0000, v91
	v_mov_b32_e32 v70, v53
	v_mov_b32_e32 v71, v55
	v_mov_b32_e32 v82, v49
	v_mov_b32_e32 v83, v51
	v_pk_fma_f32 v[56:57], v[24:25], v[98:99], v[56:57]
	s_waitcnt vmcnt(0)
	v_lshlrev_b32_e32 v90, 16, v86
	v_and_b32_e32 v91, 0xffff0000, v86
	v_lshlrev_b32_e32 v86, 16, v87
	v_and_b32_e32 v87, 0xffff0000, v87
	v_pk_fma_f32 v[60:61], v[20:21], v[84:85], v[60:61]
	v_pk_fma_f32 v[62:63], v[22:23], v[88:89], v[62:63]
	v_mov_b32_e32 v68, v52
	v_mov_b32_e32 v69, v54
	v_mov_b32_e32 v80, v48
	v_mov_b32_e32 v81, v50
	v_pk_mul_f32 v[70:71], v[70:71], v[70:71]
	v_pk_mul_f32 v[82:83], v[82:83], v[82:83]
	v_pk_fma_f32 v[56:57], v[16:17], v[90:91], v[56:57]
	v_pk_fma_f32 v[58:59], v[18:19], v[86:87], v[58:59]
	v_mul_f32_e32 v84, v61, v61
	v_mul_f32_e32 v86, v63, v63
	v_pk_fma_f32 v[68:69], v[68:69], v[68:69], v[70:71]
	v_pk_fma_f32 v[70:71], v[80:81], v[80:81], v[82:83]
	v_pk_mul_f32 v[88:89], v[56:57], v[56:57]
	v_pk_mul_f32 v[90:91], v[58:59], v[58:59]
	v_pk_fma_f32 v[84:85], v[60:61], v[60:61], v[84:85] op_sel_hi:[1,1,0]
	v_pk_fma_f32 v[86:87], v[62:63], v[62:63], v[86:87] op_sel_hi:[1,1,0]
	v_pk_add_f32 v[68:69], v[68:69], v[68:69] op_sel:[0,1] op_sel_hi:[1,0]
	v_pk_add_f32 v[70:71], v[70:71], v[70:71] op_sel:[0,1] op_sel_hi:[1,0]
	v_mov_b32_e32 v85, v90
	v_mov_b32_e32 v87, v91
	v_mov_b32_e32 v69, v88
	v_mov_b32_e32 v71, v89
	v_pk_add_f32 v[80:81], v[84:85], v[86:87]
	v_pk_add_f32 v[68:69], v[68:69], v[70:71]
	s_nop 0
	v_pk_add_f32 v[68:69], v[68:69], v[80:81]
	s_nop 0
	v_add_f32_e32 v68, v68, v69
	s_nop 1
	v_add_f32_dpp v68, v68, v68 quad_perm:[1,0,3,2] row_mask:0xf bank_mask:0xf
	s_nop 1
	v_add_f32_dpp v68, v68, v68 quad_perm:[2,3,0,1] row_mask:0xf bank_mask:0xf
	s_nop 1
	v_add_f32_dpp v68, v68, v68 row_half_mirror row_mask:0xf bank_mask:0xf
	s_nop 1
	v_add_f32_dpp v68, v68, v68 row_mirror row_mask:0xf bank_mask:0xf
	v_mov_b32_e32 v69, v68
	s_nop 1
	v_permlane16_swap_b32 v68, v69
	s_nop 1
	v_add_f32_e32 v68, v68, v69
	v_mov_b32_e32 v69, v68
	s_nop 1
	v_permlane32_swap_b32 v68, v69
	s_nop 1
	v_add_f32_e32 v68, v68, v69
	v_fmamk_f32 v68, v68, 0x3a800000, v201
	v_mul_f32_e32 v69, 0x4b800000, v68
	v_cmp_gt_f32_e32 vcc, s20, v68
	s_nop 1
	v_cndmask_b32_e32 v68, v68, v69, vcc
	v_rsq_f32_e32 v68, v68
	s_nop 0
	v_mul_f32_e32 v69, 0x45800000, v68
	v_cndmask_b32_e32 v68, v68, v69, vcc
	v_pk_mul_f32 v[52:53], v[52:53], v[68:69] op_sel_hi:[1,0]
	v_pk_mul_f32 v[54:55], v[54:55], v[68:69] op_sel_hi:[1,0]
	v_pk_mul_f32 v[70:71], v[48:49], v[68:69] op_sel_hi:[1,0]
	v_pk_mul_f32 v[80:81], v[50:51], v[68:69] op_sel_hi:[1,0]
	v_pk_mul_f32 v[60:61], v[60:61], v[68:69] op_sel_hi:[1,0]
	v_pk_mul_f32 v[62:63], v[62:63], v[68:69] op_sel_hi:[1,0]
	v_pk_mul_f32 v[82:83], v[56:57], v[68:69] op_sel_hi:[1,0]
	v_pk_mul_f32 v[68:69], v[58:59], v[68:69] op_sel_hi:[1,0]
	v_pk_mul_f32 v[50:51], v[2:3], v[54:55]
	v_pk_mul_f32 v[48:49], v[0:1], v[52:53]
	v_pk_mul_f32 v[54:55], v[6:7], v[80:81]
	v_pk_mul_f32 v[52:53], v[4:5], v[70:71]
	v_pk_mul_f32 v[58:59], v[10:11], v[62:63]
	v_pk_mul_f32 v[56:57], v[8:9], v[60:61]
	v_pk_mul_f32 v[62:63], v[14:15], v[68:69]
	v_pk_mul_f32 v[60:61], v[12:13], v[82:83]
	global_store_dwordx4 v[66:67], v[48:51], off offset:-3072 nt
	global_store_dwordx4 v[66:67], v[52:55], off offset:-2048 nt
	global_store_dwordx4 v[66:67], v[56:59], off offset:-1024 nt
	global_store_dwordx4 v[66:67], v[60:63], off nt
	v_lshl_add_u64 v[66:67], v[66:67], 0, s[14:15]
	s_andn2_b64 exec, exec, s[16:17]
	s_cbranch_execnz .LBB0_20
	s_or_b64 exec, exec, s[16:17]
	s_cmp_lg_u32 s100, 0
	s_cbranch_scc1 .Lnt_done_f
	s_mov_b32 s100, 1
	s_mov_b64 s[16:17], 0
	v_add_u32_e32 v79, 0x700, v79
	v_add_u32_e32 v72, 0x800, v72
	s_mov_b32 vcc_lo, 0x380000
	s_mov_b32 vcc_hi, 0
	v_lshl_add_u64 v[64:65], v[64:65], 0, vcc
	s_mov_b32 vcc_lo, 0x700000
	v_lshl_add_u64 v[66:67], v[66:67], 0, vcc
	s_branch .LBB0_20

.Lnrm1_go_a:
	v_lshlrev_b32_e32 v106, 16, v96
	v_and_b32_e32 v107, 0xffff0000, v96
	v_lshlrev_b32_e32 v108, 16, v97
	v_and_b32_e32 v109, 0xffff0000, v97
	v_pk_fma_f32 v[68:69], v[44:45], v[106:107], v[68:69]
	v_pk_fma_f32 v[70:71], v[46:47], v[108:109], v[70:71]
	v_lshlrev_b32_e32 v106, 16, v98
	v_and_b32_e32 v107, 0xffff0000, v98
	v_lshlrev_b32_e32 v108, 16, v99
	v_and_b32_e32 v109, 0xffff0000, v99
	v_pk_fma_f32 v[72:73], v[40:41], v[106:107], v[72:73]
	v_pk_fma_f32 v[74:75], v[42:43], v[108:109], v[74:75]
	v_lshlrev_b32_e32 v106, 16, v100
	v_and_b32_e32 v107, 0xffff0000, v100
	v_lshlrev_b32_e32 v108, 16, v101
	v_and_b32_e32 v109, 0xffff0000, v101
	v_pk_fma_f32 v[88:89], v[36:37], v[106:107], v[88:89]
	v_pk_fma_f32 v[90:91], v[38:39], v[108:109], v[90:91]
	v_lshlrev_b32_e32 v106, 16, v102
	v_and_b32_e32 v107, 0xffff0000, v102
	v_lshlrev_b32_e32 v108, 16, v103
	v_and_b32_e32 v109, 0xffff0000, v103
	v_pk_fma_f32 v[92:93], v[32:33], v[106:107], v[92:93]
	v_pk_fma_f32 v[94:95], v[34:35], v[108:109], v[94:95]
	v_mul_f32_e32 v111, v69, v69
	v_fma_f32 v110, v68, v68, v111
	v_mul_f32_e32 v111, v71, v71
	v_fma_f32 v111, v70, v70, v111
	v_add_f32_e32 v112, v110, v111
	v_mul_f32_e32 v111, v73, v73
	v_fma_f32 v110, v72, v72, v111
	v_mul_f32_e32 v111, v75, v75
	v_fma_f32 v111, v74, v74, v111
	v_add_f32_e32 v113, v110, v111
	v_mul_f32_e32 v111, v89, v89
	v_fma_f32 v110, v88, v88, v111
	v_mul_f32_e32 v111, v91, v91
	v_fma_f32 v111, v90, v90, v111
	v_add_f32_e32 v114, v110, v111
	v_mul_f32_e32 v110, v92, v92
	v_mul_f32_e32 v111, v93, v93
	v_add_f32_e32 v110, v110, v111
	v_mul_f32_e32 v111, v94, v94
	v_mul_f32_e32 v115, v95, v95
	v_add_f32_e32 v111, v111, v115
	v_add_f32_e32 v115, v110, v111
	v_add_f32_e32 v112, v112, v113
	v_add_f32_e32 v112, v112, v114
	v_add_f32_e32 v112, v112, v115
	s_nop 1
	v_add_f32_dpp v112, v112, v112 quad_perm:[1,0,3,2] row_mask:0xf bank_mask:0xf
	s_nop 1
	v_add_f32_dpp v112, v112, v112 quad_perm:[2,3,0,1] row_mask:0xf bank_mask:0xf
	s_nop 1
	v_add_f32_dpp v112, v112, v112 row_half_mirror row_mask:0xf bank_mask:0xf
	s_nop 1
	v_add_f32_dpp v112, v112, v112 row_mirror row_mask:0xf bank_mask:0xf
	v_mov_b32_e32 v124, v112
	s_nop 1
	v_permlane16_swap_b32 v112, v124
	s_nop 1
	v_add_f32_e32 v112, v112, v124
	v_mov_b32_e32 v124, v112
	s_nop 1
	v_permlane32_swap_b32 v112, v124
	s_nop 1
	v_add_f32_e32 v112, v112, v124
	v_fmamk_f32 v112, v112, 0x3a800000, v201
	v_cmp_gt_f32_e32 vcc, s16, v112
	v_mul_f32_e32 v124, 0x4b800000, v112
	s_nop 0
	v_cndmask_b32_e32 v112, v112, v124, vcc
	v_rsq_f32_e32 v116, v112
	s_nop 0
	v_mul_f32_e32 v124, 0x45800000, v116
	v_cndmask_b32_e32 v116, v116, v124, vcc
	v_pk_mul_f32 v[106:107], v[68:69], v[116:117] op_sel_hi:[1,0]
	v_pk_mul_f32 v[108:109], v[70:71], v[116:117] op_sel_hi:[1,0]
	v_pk_mul_f32 v[106:107], v[0:1], v[106:107]
	v_pk_mul_f32 v[108:109], v[2:3], v[108:109]
	v_pk_fma_f32 v[106:107], v[50:51], v[106:107], v[16:17]
	v_pk_fma_f32 v[108:109], v[48:49], v[108:109], v[18:19]
	v_cvt_pk_bf16_f32 v120, v106, v107
	v_cvt_pk_bf16_f32 v121, v108, v109
	global_store_dwordx2 v[122:123], v[120:121], off
	v_pk_mul_f32 v[106:107], v[72:73], v[116:117] op_sel_hi:[1,0]
	v_pk_mul_f32 v[108:109], v[74:75], v[116:117] op_sel_hi:[1,0]
	v_pk_mul_f32 v[106:107], v[4:5], v[106:107]
	v_pk_mul_f32 v[108:109], v[6:7], v[108:109]
	v_pk_fma_f32 v[106:107], v[54:55], v[106:107], v[20:21]
	v_pk_fma_f32 v[108:109], v[52:53], v[108:109], v[22:23]
	v_cvt_pk_bf16_f32 v118, v106, v107
	v_cvt_pk_bf16_f32 v119, v108, v109
	global_store_dwordx2 v[122:123], v[118:119], off offset:512
	v_pk_mul_f32 v[106:107], v[88:89], v[116:117] op_sel_hi:[1,0]
	v_pk_mul_f32 v[108:109], v[90:91], v[116:117] op_sel_hi:[1,0]
	v_pk_mul_f32 v[106:107], v[8:9], v[106:107]
	v_pk_mul_f32 v[108:109], v[10:11], v[108:109]
	v_pk_fma_f32 v[106:107], v[58:59], v[106:107], v[24:25]
	v_pk_fma_f32 v[108:109], v[56:57], v[108:109], v[26:27]
	v_cvt_pk_bf16_f32 v120, v106, v107
	v_cvt_pk_bf16_f32 v121, v108, v109
	global_store_dwordx2 v[122:123], v[120:121], off offset:1024
	v_pk_mul_f32 v[106:107], v[92:93], v[116:117] op_sel_hi:[1,0]
	v_pk_mul_f32 v[108:109], v[94:95], v[116:117] op_sel_hi:[1,0]
	v_pk_mul_f32 v[106:107], v[12:13], v[106:107]
	v_pk_mul_f32 v[108:109], v[14:15], v[108:109]
	v_pk_fma_f32 v[106:107], v[62:63], v[106:107], v[28:29]
	v_pk_fma_f32 v[108:109], v[60:61], v[108:109], v[30:31]
	v_cvt_pk_bf16_f32 v118, v106, v107
	v_cvt_pk_bf16_f32 v119, v108, v109
	global_store_dwordx2 v[122:123], v[118:119], off offset:1536
	s_and_b64 vcc, exec, s[12:13]
	s_cbranch_vccz .Lnrm1_done
	v_add_co_u32_e32 v122, vcc, 0xec800000, v64
	v_add_u32_e32 v86, 32, v86
	s_nop 0
	v_addc_co_u32_e32 v123, vcc, -1, v65, vcc
	v_lshl_add_u64 v[66:67], v[66:67], 0, s[6:7]
	v_lshl_add_u64 v[64:65], v[64:65], 0, s[2:3]
	v_cmp_lt_i32_e64 s[12:13], v86, v77
	s_nop 1
	s_and_b64 vcc, exec, s[12:13]
	s_cbranch_vccz .Lnrm1_nonext_b
	global_load_dwordx4 v[68:71], v[66:67], off offset:-3072 nt
	global_load_dwordx4 v[72:75], v[66:67], off offset:-2048 nt
	global_load_dwordx4 v[88:91], v[66:67], off offset:-1024 nt
	global_load_dwordx4 v[92:95], v[66:67], off nt
	global_load_dwordx2 v[96:97], v[64:65], off nt
	global_load_dwordx2 v[98:99], v[64:65], off offset:512 nt
	global_load_dwordx2 v[100:101], v[64:65], off offset:1024 nt
	global_load_dwordx2 v[102:103], v[64:65], off offset:1536 nt
	s_waitcnt vmcnt(12)
	s_branch .Lnrm1_go_b

.Lnrm1_go_b:
	v_lshlrev_b32_e32 v106, 16, v156
	v_and_b32_e32 v107, 0xffff0000, v156
	v_lshlrev_b32_e32 v108, 16, v157
	v_and_b32_e32 v109, 0xffff0000, v157
	v_pk_fma_f32 v[140:141], v[44:45], v[106:107], v[140:141]
	v_pk_fma_f32 v[142:143], v[46:47], v[108:109], v[142:143]
	v_lshlrev_b32_e32 v106, 16, v158
	v_and_b32_e32 v107, 0xffff0000, v158
	v_lshlrev_b32_e32 v108, 16, v159
	v_and_b32_e32 v109, 0xffff0000, v159
	v_pk_fma_f32 v[144:145], v[40:41], v[106:107], v[144:145]
	v_pk_fma_f32 v[146:147], v[42:43], v[108:109], v[146:147]
	v_lshlrev_b32_e32 v106, 16, v160
	v_and_b32_e32 v107, 0xffff0000, v160
	v_lshlrev_b32_e32 v108, 16, v161
	v_and_b32_e32 v109, 0xffff0000, v161
	v_pk_fma_f32 v[148:149], v[36:37], v[106:107], v[148:149]
	v_pk_fma_f32 v[150:151], v[38:39], v[108:109], v[150:151]
	v_lshlrev_b32_e32 v106, 16, v162
	v_and_b32_e32 v107, 0xffff0000, v162
	v_lshlrev_b32_e32 v108, 16, v163
	v_and_b32_e32 v109, 0xffff0000, v163
	v_pk_fma_f32 v[152:153], v[32:33], v[106:107], v[152:153]
	v_pk_fma_f32 v[154:155], v[34:35], v[108:109], v[154:155]
	v_mul_f32_e32 v111, v141, v141
	v_fma_f32 v110, v140, v140, v111
	v_mul_f32_e32 v111, v143, v143
	v_fma_f32 v111, v142, v142, v111
	v_add_f32_e32 v112, v110, v111
	v_mul_f32_e32 v111, v145, v145
	v_fma_f32 v110, v144, v144, v111
	v_mul_f32_e32 v111, v147, v147
	v_fma_f32 v111, v146, v146, v111
	v_add_f32_e32 v113, v110, v111
	v_mul_f32_e32 v111, v149, v149
	v_fma_f32 v110, v148, v148, v111
	v_mul_f32_e32 v111, v151, v151
	v_fma_f32 v111, v150, v150, v111
	v_add_f32_e32 v114, v110, v111
	v_mul_f32_e32 v110, v152, v152
	v_mul_f32_e32 v111, v153, v153
	v_add_f32_e32 v110, v110, v111
	v_mul_f32_e32 v111, v154, v154
	v_mul_f32_e32 v115, v155, v155
	v_add_f32_e32 v111, v111, v115
	v_add_f32_e32 v115, v110, v111
	v_add_f32_e32 v112, v112, v113
	v_add_f32_e32 v112, v112, v114
	v_add_f32_e32 v112, v112, v115
	s_nop 1
	v_add_f32_dpp v112, v112, v112 quad_perm:[1,0,3,2] row_mask:0xf bank_mask:0xf
	s_nop 1
	v_add_f32_dpp v112, v112, v112 quad_perm:[2,3,0,1] row_mask:0xf bank_mask:0xf
	s_nop 1
	v_add_f32_dpp v112, v112, v112 row_half_mirror row_mask:0xf bank_mask:0xf
	s_nop 1
	v_add_f32_dpp v112, v112, v112 row_mirror row_mask:0xf bank_mask:0xf
	v_mov_b32_e32 v124, v112
	s_nop 1
	v_permlane16_swap_b32 v112, v124
	s_nop 1
	v_add_f32_e32 v112, v112, v124
	v_mov_b32_e32 v124, v112
	s_nop 1
	v_permlane32_swap_b32 v112, v124
	s_nop 1
	v_add_f32_e32 v112, v112, v124
	v_fmamk_f32 v112, v112, 0x3a800000, v201
	v_cmp_gt_f32_e32 vcc, s16, v112
	v_mul_f32_e32 v124, 0x4b800000, v112
	s_nop 0
	v_cndmask_b32_e32 v112, v112, v124, vcc
	v_rsq_f32_e32 v116, v112
	s_nop 0
	v_mul_f32_e32 v124, 0x45800000, v116
	v_cndmask_b32_e32 v116, v116, v124, vcc
	v_pk_mul_f32 v[106:107], v[140:141], v[116:117] op_sel_hi:[1,0]
	v_pk_mul_f32 v[108:109], v[142:143], v[116:117] op_sel_hi:[1,0]
	v_pk_mul_f32 v[106:107], v[0:1], v[106:107]
	v_pk_mul_f32 v[108:109], v[2:3], v[108:109]
	v_pk_fma_f32 v[106:107], v[50:51], v[106:107], v[16:17]
	v_pk_fma_f32 v[108:109], v[48:49], v[108:109], v[18:19]
	v_cvt_pk_bf16_f32 v120, v106, v107
	v_cvt_pk_bf16_f32 v121, v108, v109
	global_store_dwordx2 v[122:123], v[120:121], off
	v_pk_mul_f32 v[106:107], v[144:145], v[116:117] op_sel_hi:[1,0]
	v_pk_mul_f32 v[108:109], v[146:147], v[116:117] op_sel_hi:[1,0]
	v_pk_mul_f32 v[106:107], v[4:5], v[106:107]
	v_pk_mul_f32 v[108:109], v[6:7], v[108:109]
	v_pk_fma_f32 v[106:107], v[54:55], v[106:107], v[20:21]
	v_pk_fma_f32 v[108:109], v[52:53], v[108:109], v[22:23]
	v_cvt_pk_bf16_f32 v118, v106, v107
	v_cvt_pk_bf16_f32 v119, v108, v109
	global_store_dwordx2 v[122:123], v[118:119], off offset:512
	v_pk_mul_f32 v[106:107], v[148:149], v[116:117] op_sel_hi:[1,0]
	v_pk_mul_f32 v[108:109], v[150:151], v[116:117] op_sel_hi:[1,0]
	v_pk_mul_f32 v[106:107], v[8:9], v[106:107]
	v_pk_mul_f32 v[108:109], v[10:11], v[108:109]
	v_pk_fma_f32 v[106:107], v[58:59], v[106:107], v[24:25]
	v_pk_fma_f32 v[108:109], v[56:57], v[108:109], v[26:27]
	v_cvt_pk_bf16_f32 v120, v106, v107
	v_cvt_pk_bf16_f32 v121, v108, v109
	global_store_dwordx2 v[122:123], v[120:121], off offset:1024
	v_pk_mul_f32 v[106:107], v[152:153], v[116:117] op_sel_hi:[1,0]
	v_pk_mul_f32 v[108:109], v[154:155], v[116:117] op_sel_hi:[1,0]
	v_pk_mul_f32 v[106:107], v[12:13], v[106:107]
	v_pk_mul_f32 v[108:109], v[14:15], v[108:109]
	v_pk_fma_f32 v[106:107], v[62:63], v[106:107], v[28:29]
	v_pk_fma_f32 v[108:109], v[60:61], v[108:109], v[30:31]
	v_cvt_pk_bf16_f32 v118, v106, v107
	v_cvt_pk_bf16_f32 v119, v108, v109
	global_store_dwordx2 v[122:123], v[118:119], off offset:1536
	s_and_b64 vcc, exec, s[12:13]
	s_cbranch_vccnz .Lnrm1_loop

.LBB0_386:
	v_add_co_u32_e32 v100, vcc, 0xec800000, v98
	v_lshl_add_u64 v[76:77], s[6:7], 0, v[80:81]
	s_nop 0
	v_addc_co_u32_e32 v101, vcc, -1, v99, vcc
	global_load_dwordx4 v[64:67], v[76:77], off nt
	global_load_dwordx4 v[68:71], v[76:77], off offset:1024 nt
	global_load_dwordx4 v[72:75], v[76:77], off offset:2048 nt
	s_nop 0
	global_load_dwordx4 v[76:79], v[76:77], off offset:3072 nt
	s_nop 0
	global_load_dwordx2 v[102:103], v[98:99], off nt
	global_load_dwordx2 v[112:113], v[98:99], off offset:512 nt
	global_load_dwordx2 v[114:115], v[98:99], off offset:1024 nt
	global_load_dwordx2 v[116:117], v[98:99], off offset:1536 nt
	global_load_dwordx2 v[118:119], v[100:101], off nt
	v_add_u32_e32 v111, 32, v111
	s_waitcnt vmcnt(4)
	v_lshlrev_b32_e32 v120, 16, v102
	v_and_b32_e32 v121, 0xffff0000, v102
	v_lshlrev_b32_e32 v102, 16, v103
	v_and_b32_e32 v103, 0xffff0000, v103
	v_pk_fma_f32 v[66:67], v[62:63], v[102:103], v[66:67]
	s_waitcnt vmcnt(0)
	v_lshlrev_b32_e32 v102, 16, v119
	v_and_b32_e32 v103, 0xffff0000, v119
	v_pk_fma_f32 v[66:67], v[58:59], v[102:103], v[66:67]
	v_add_co_u32_e32 v102, vcc, s60, v98
	v_pk_fma_f32 v[64:65], v[60:61], v[120:121], v[64:65]
	s_nop 0
	v_addc_co_u32_e32 v103, vcc, -1, v99, vcc
	v_lshlrev_b32_e32 v120, 16, v118
	v_and_b32_e32 v121, 0xffff0000, v118
	global_load_dwordx2 v[118:119], v[102:103], off offset:-3584 nt
	v_pk_fma_f32 v[64:65], v[56:57], v[120:121], v[64:65]
	v_lshlrev_b32_e32 v120, 16, v112
	v_and_b32_e32 v121, 0xffff0000, v112
	v_lshlrev_b32_e32 v112, 16, v113
	v_and_b32_e32 v113, 0xffff0000, v113
	v_pk_fma_f32 v[70:71], v[54:55], v[112:113], v[70:71]
	v_pk_fma_f32 v[68:69], v[52:53], v[120:121], v[68:69]
	v_lshl_add_u64 v[98:99], v[98:99], 0, s[14:15]
	s_waitcnt vmcnt(0)
	v_lshlrev_b32_e32 v112, 16, v119
	v_and_b32_e32 v113, 0xffff0000, v119
	v_pk_fma_f32 v[70:71], v[46:47], v[112:113], v[70:71]
	global_load_dwordx2 v[112:113], v[102:103], off offset:-3072 nt
	v_lshlrev_b32_e32 v120, 16, v118
	v_and_b32_e32 v121, 0xffff0000, v118
	v_lshlrev_b32_e32 v118, 16, v114
	v_and_b32_e32 v119, 0xffff0000, v114
	v_lshlrev_b32_e32 v114, 16, v115
	v_and_b32_e32 v115, 0xffff0000, v115
	v_pk_fma_f32 v[72:73], v[36:37], v[118:119], v[72:73]
	v_pk_fma_f32 v[74:75], v[38:39], v[114:115], v[74:75]
	v_lshlrev_b32_e32 v114, 16, v116
	v_and_b32_e32 v115, 0xffff0000, v116
	v_pk_fma_f32 v[76:77], v[32:33], v[114:115], v[76:77]
	v_pk_fma_f32 v[68:69], v[44:45], v[120:121], v[68:69]
	s_waitcnt vmcnt(0)
	v_lshlrev_b32_e32 v118, 16, v112
	v_and_b32_e32 v119, 0xffff0000, v112
	v_lshlrev_b32_e32 v112, 16, v113
	v_and_b32_e32 v113, 0xffff0000, v113
	v_pk_fma_f32 v[74:75], v[42:43], v[112:113], v[74:75]
	global_load_dwordx2 v[112:113], v[102:103], off offset:-2560 nt
	v_mov_b32_e32 v116, v69
	v_pk_fma_f32 v[72:73], v[40:41], v[118:119], v[72:73]
	v_mul_f32_e32 v118, v75, v75
	v_pk_fma_f32 v[118:119], v[74:75], v[74:75], v[118:119] op_sel_hi:[1,1,0]
	s_waitcnt vmcnt(0)
	v_lshlrev_b32_e32 v114, 16, v112
	v_and_b32_e32 v115, 0xffff0000, v112
	v_pk_fma_f32 v[76:77], v[48:49], v[114:115], v[76:77]
	v_lshlrev_b32_e32 v114, 16, v117
	v_and_b32_e32 v115, 0xffff0000, v117
	v_pk_fma_f32 v[78:79], v[34:35], v[114:115], v[78:79]
	v_lshlrev_b32_e32 v112, 16, v113
	v_and_b32_e32 v113, 0xffff0000, v113
	v_mov_b32_e32 v114, v65
	v_mov_b32_e32 v115, v67
	v_pk_fma_f32 v[78:79], v[50:51], v[112:113], v[78:79]
	v_mov_b32_e32 v112, v64
	v_mov_b32_e32 v113, v66
	v_pk_mul_f32 v[114:115], v[114:115], v[114:115]
	v_mov_b32_e32 v117, v71
	v_pk_fma_f32 v[112:113], v[112:113], v[112:113], v[114:115]
	v_mov_b32_e32 v114, v68
	v_mov_b32_e32 v115, v70
	v_pk_mul_f32 v[116:117], v[116:117], v[116:117]
	v_pk_add_f32 v[112:113], v[112:113], v[112:113] op_sel:[0,1] op_sel_hi:[1,0]
	v_pk_fma_f32 v[114:115], v[114:115], v[114:115], v[116:117]
	v_mul_f32_e32 v116, v73, v73
	v_pk_add_f32 v[114:115], v[114:115], v[114:115] op_sel:[0,1] op_sel_hi:[1,0]
	v_pk_fma_f32 v[116:117], v[72:73], v[72:73], v[116:117] op_sel_hi:[1,1,0]
	v_pk_mul_f32 v[120:121], v[76:77], v[76:77]
	v_pk_mul_f32 v[122:123], v[78:79], v[78:79]
	v_mov_b32_e32 v113, v120
	v_mov_b32_e32 v115, v121
	v_mov_b32_e32 v117, v122
	v_mov_b32_e32 v119, v123
	v_pk_add_f32 v[112:113], v[112:113], v[114:115]
	v_pk_add_f32 v[114:115], v[116:117], v[118:119]
	s_nop 0
	v_pk_add_f32 v[112:113], v[112:113], v[114:115]
	s_nop 0
	v_add_f32_e32 v112, v112, v113
	s_nop 1
	v_add_f32_dpp v112, v112, v112 quad_perm:[1,0,3,2] row_mask:0xf bank_mask:0xf
	s_nop 1
	v_add_f32_dpp v112, v112, v112 quad_perm:[2,3,0,1] row_mask:0xf bank_mask:0xf
	s_nop 1
	v_add_f32_dpp v112, v112, v112 row_half_mirror row_mask:0xf bank_mask:0xf
	s_nop 1
	v_add_f32_dpp v112, v112, v112 row_mirror row_mask:0xf bank_mask:0xf
	v_mov_b32_e32 v113, v112
	s_nop 1
	v_permlane16_swap_b32 v112, v113
	s_nop 1
	v_add_f32_e32 v112, v112, v113
	v_mov_b32_e32 v113, v112
	s_nop 1
	v_permlane32_swap_b32 v112, v113
	s_nop 1
	v_add_f32_e32 v112, v112, v113
	v_fmamk_f32 v112, v112, 0x3a800000, v201
	v_cmp_gt_f32_e32 vcc, s20, v112
	v_mul_f32_e32 v113, 0x4b800000, v112
	s_nop 0
	v_cndmask_b32_e32 v112, v112, v113, vcc
	v_rsq_f32_e32 v114, v112
	v_lshl_add_u64 v[112:113], s[76:77], 0, v[80:81]
	global_store_dwordx4 v[112:113], v[64:67], off nt
	global_store_dwordx4 v[112:113], v[68:71], off offset:1024 nt
	global_store_dwordx4 v[112:113], v[72:75], off offset:2048 nt
	global_store_dwordx4 v[112:113], v[76:79], off offset:3072 nt
	v_lshl_add_u64 v[80:81], v[80:81], 0, s[12:13]
	v_mul_f32_e32 v115, 0x45800000, v114
	v_cndmask_b32_e32 v112, v114, v115, vcc
	v_pk_mul_f32 v[66:67], v[66:67], v[112:113] op_sel_hi:[1,0]
	v_pk_mul_f32 v[64:65], v[64:65], v[112:113] op_sel_hi:[1,0]
	v_pk_mul_f32 v[66:67], v[2:3], v[66:67]
	v_pk_mul_f32 v[64:65], v[0:1], v[64:65]
	v_pk_fma_f32 v[66:67], v[82:83], v[66:67], v[18:19]
	v_pk_fma_f32 v[64:65], v[84:85], v[64:65], v[16:17]
	v_cmp_ge_i32_e32 vcc, v111, v104
	v_cvt_pk_bf16_f32 v64, v64, v65
	v_cvt_pk_bf16_f32 v65, v66, v67
	global_store_dwordx2 v[100:101], v[64:65], off
	v_pk_mul_f32 v[64:65], v[70:71], v[112:113] op_sel_hi:[1,0]
	v_pk_mul_f32 v[66:67], v[68:69], v[112:113] op_sel_hi:[1,0]
	v_pk_mul_f32 v[64:65], v[6:7], v[64:65]
	v_pk_mul_f32 v[66:67], v[4:5], v[66:67]
	v_pk_fma_f32 v[64:65], v[86:87], v[64:65], v[22:23]
	v_pk_fma_f32 v[66:67], v[88:89], v[66:67], v[20:21]
	s_or_b64 s[16:17], vcc, s[16:17]
	v_cvt_pk_bf16_f32 v66, v66, v67
	v_cvt_pk_bf16_f32 v67, v64, v65
	global_store_dwordx2 v[102:103], v[66:67], off offset:-3584
	v_pk_mul_f32 v[64:65], v[74:75], v[112:113] op_sel_hi:[1,0]
	v_pk_mul_f32 v[66:67], v[72:73], v[112:113] op_sel_hi:[1,0]
	v_pk_mul_f32 v[64:65], v[10:11], v[64:65]
	v_pk_mul_f32 v[66:67], v[8:9], v[66:67]
	v_pk_fma_f32 v[64:65], v[90:91], v[64:65], v[26:27]
	v_pk_fma_f32 v[66:67], v[92:93], v[66:67], v[24:25]
	s_nop 0
	v_cvt_pk_bf16_f32 v66, v66, v67
	v_cvt_pk_bf16_f32 v67, v64, v65
	global_store_dwordx2 v[102:103], v[66:67], off offset:-3072
	v_pk_mul_f32 v[64:65], v[78:79], v[112:113] op_sel_hi:[1,0]
	v_pk_mul_f32 v[66:67], v[76:77], v[112:113] op_sel_hi:[1,0]
	v_pk_mul_f32 v[64:65], v[14:15], v[64:65]
	v_pk_mul_f32 v[66:67], v[12:13], v[66:67]
	v_pk_fma_f32 v[64:65], v[94:95], v[64:65], v[30:31]
	v_pk_fma_f32 v[66:67], v[96:97], v[66:67], v[28:29]
	s_nop 0
	v_cvt_pk_bf16_f32 v66, v66, v67
	v_cvt_pk_bf16_f32 v67, v64, v65
	global_store_dwordx2 v[102:103], v[66:67], off offset:-2560
	s_andn2_b64 exec, exec, s[16:17]
	s_cbranch_execnz .LBB0_386
	s_or_b64 exec, exec, s[16:17]
	s_cmp_lg_u32 s100, 0
	s_cbranch_scc1 .Lnt_done_n2
	s_mov_b32 s100, 1
	s_mov_b64 s[16:17], 0
	v_add_u32_e32 v111, 0x700, v111
	v_add_u32_e32 v104, 0x800, v104
	s_mov_b32 vcc_lo, 0x380000
	s_mov_b32 vcc_hi, 0
	v_lshl_add_u64 v[98:99], v[98:99], 0, vcc
	s_mov_b32 vcc_lo, 0x700000
	v_lshl_add_u64 v[80:81], v[80:81], 0, vcc
	s_branch .LBB0_386

.LBB0_392:
	global_load_dwordx4 v[60:63], v[34:35], off offset:-3072 nt
	global_load_dwordx4 v[64:67], v[34:35], off offset:-2048 nt
	global_load_dwordx4 v[68:71], v[34:35], off offset:-1024 nt
	global_load_dwordx4 v[72:75], v[34:35], off nt
	v_add_u32_e32 v59, 32, v59
	v_cmp_ge_i32_e32 vcc, v59, v52
	s_or_b64 s[12:13], vcc, s[12:13]
	v_lshl_add_u64 v[34:35], v[34:35], 0, s[6:7]
	s_waitcnt vmcnt(3)
	v_pk_mul_f32 v[76:77], v[62:63], v[62:63]
	v_pk_mul_f32 v[78:79], v[60:61], v[60:61]
	s_waitcnt vmcnt(2)
	v_pk_mul_f32 v[80:81], v[66:67], v[66:67]
	v_pk_mul_f32 v[82:83], v[64:65], v[64:65]
	v_pk_mov_b32 v[88:89], v[78:79], v[76:77] op_sel:[1,0]
	v_mov_b32_e32 v79, v77
	v_pk_mov_b32 v[76:77], v[82:83], v[80:81] op_sel:[1,0]
	v_mov_b32_e32 v83, v81
	s_waitcnt vmcnt(0)
	v_mul_f32_e32 v87, v72, v72
	v_mul_f32_e32 v84, v69, v69
	v_mul_f32_e32 v86, v71, v71
	v_pk_add_f32 v[78:79], v[88:89], v[78:79]
	v_pk_add_f32 v[76:77], v[76:77], v[82:83]
	v_mul_f32_e32 v90, v73, v73
	v_mul_f32_e32 v91, v74, v74
	v_mul_f32_e32 v92, v75, v75
	v_pk_fma_f32 v[80:81], v[68:69], v[68:69], v[84:85] op_sel_hi:[1,1,0]
	v_pk_fma_f32 v[84:85], v[70:71], v[70:71], v[86:87] op_sel_hi:[1,1,0]
	v_pk_add_f32 v[78:79], v[78:79], v[78:79] op_sel:[0,1] op_sel_hi:[1,0]
	v_pk_add_f32 v[76:77], v[76:77], v[76:77] op_sel:[0,1] op_sel_hi:[1,0]
	v_mov_b32_e32 v81, v91
	v_mov_b32_e32 v85, v92
	v_mov_b32_e32 v79, v87
	v_mov_b32_e32 v77, v90
	v_pk_add_f32 v[80:81], v[80:81], v[84:85]
	v_pk_add_f32 v[76:77], v[78:79], v[76:77]
	s_nop 0
	v_pk_add_f32 v[76:77], v[76:77], v[80:81]
	s_nop 0
	v_add_f32_e32 v76, v76, v77
	s_nop 1
	v_add_f32_dpp v76, v76, v76 quad_perm:[1,0,3,2] row_mask:0xf bank_mask:0xf
	s_nop 1
	v_add_f32_dpp v76, v76, v76 quad_perm:[2,3,0,1] row_mask:0xf bank_mask:0xf
	s_nop 1
	v_add_f32_dpp v76, v76, v76 row_half_mirror row_mask:0xf bank_mask:0xf
	s_nop 1
	v_add_f32_dpp v76, v76, v76 row_mirror row_mask:0xf bank_mask:0xf
	v_mov_b32_e32 v77, v76
	s_nop 1
	v_permlane16_swap_b32 v76, v77
	s_nop 1
	v_add_f32_e32 v76, v76, v77
	v_mov_b32_e32 v77, v76
	s_nop 1
	v_permlane32_swap_b32 v76, v77
	s_nop 1
	v_add_f32_e32 v76, v76, v77
	v_fmamk_f32 v76, v76, 0x3a800000, v201
	v_mul_f32_e32 v77, 0x4b800000, v76
	v_cmp_gt_f32_e32 vcc, s16, v76
	s_nop 1
	v_cndmask_b32_e32 v76, v76, v77, vcc
	v_rsq_f32_e32 v76, v76
	s_nop 0
	v_mul_f32_e32 v77, 0x45800000, v76
	v_cndmask_b32_e32 v76, v76, v77, vcc
	v_pk_mul_f32 v[62:63], v[62:63], v[76:77] op_sel_hi:[1,0]
	v_pk_mul_f32 v[60:61], v[60:61], v[76:77] op_sel_hi:[1,0]
	v_pk_mul_f32 v[66:67], v[66:67], v[76:77] op_sel_hi:[1,0]
	v_pk_mul_f32 v[64:65], v[64:65], v[76:77] op_sel_hi:[1,0]
	v_pk_mul_f32 v[70:71], v[70:71], v[76:77] op_sel_hi:[1,0]
	v_pk_mul_f32 v[68:69], v[68:69], v[76:77] op_sel_hi:[1,0]
	v_pk_mul_f32 v[74:75], v[74:75], v[76:77] op_sel_hi:[1,0]
	v_pk_mul_f32 v[72:73], v[72:73], v[76:77] op_sel_hi:[1,0]
	v_pk_mul_f32 v[60:61], v[0:1], v[60:61]
	v_pk_mul_f32 v[62:63], v[2:3], v[62:63]
	v_pk_mul_f32 v[64:65], v[4:5], v[64:65]
	v_pk_mul_f32 v[66:67], v[6:7], v[66:67]
	v_pk_mul_f32 v[68:69], v[8:9], v[68:69]
	v_pk_mul_f32 v[70:71], v[10:11], v[70:71]
	v_pk_mul_f32 v[72:73], v[12:13], v[72:73]
	v_pk_mul_f32 v[74:75], v[14:15], v[74:75]
	v_pk_fma_f32 v[62:63], v[36:37], v[62:63], v[18:19]
	v_pk_fma_f32 v[60:61], v[38:39], v[60:61], v[16:17]
	v_pk_fma_f32 v[66:67], v[40:41], v[66:67], v[22:23]
	v_pk_fma_f32 v[64:65], v[42:43], v[64:65], v[20:21]
	v_pk_fma_f32 v[70:71], v[44:45], v[70:71], v[26:27]
	v_pk_fma_f32 v[68:69], v[46:47], v[68:69], v[24:25]
	v_pk_fma_f32 v[74:75], v[48:49], v[74:75], v[30:31]
	v_pk_fma_f32 v[72:73], v[50:51], v[72:73], v[28:29]
	v_cvt_pk_bf16_f32 v60, v60, v61
	v_cvt_pk_bf16_f32 v61, v62, v63
	v_cvt_pk_bf16_f32 v62, v64, v65
	v_cvt_pk_bf16_f32 v63, v66, v67
	v_cvt_pk_bf16_f32 v64, v68, v69
	v_cvt_pk_bf16_f32 v65, v70, v71
	v_cvt_pk_bf16_f32 v66, v72, v73
	v_cvt_pk_bf16_f32 v67, v74, v75
	global_store_dwordx2 v[32:33], v[60:61], off
	global_store_dwordx2 v[32:33], v[62:63], off offset:512
	global_store_dwordx2 v[32:33], v[64:65], off offset:1024
	global_store_dwordx2 v[32:33], v[66:67], off offset:1536
	v_lshl_add_u64 v[32:33], v[32:33], 0, s[0:1]
	s_andn2_b64 exec, exec, s[12:13]
	s_cbranch_execnz .LBB0_392
	s_or_b64 exec, exec, s[12:13]
	s_cmp_lg_u32 s100, 0
	s_cbranch_scc1 .Lnt_done_n0
	s_mov_b32 s100, 1
	s_mov_b64 s[12:13], 0
	v_add_u32_e32 v59, 0x700, v59
	v_add_u32_e32 v52, 0x800, v52
	s_mov_b32 vcc_lo, 0x380000
	s_mov_b32 vcc_hi, 0
	v_lshl_add_u64 v[32:33], v[32:33], 0, vcc
	s_mov_b32 vcc_lo, 0x700000
	v_lshl_add_u64 v[34:35], v[34:35], 0, vcc
	s_branch .LBB0_392
